# s5_gen (prep copy) steps 2 and 5 rewritten by hand (batched LDS reads, line-coalesced M scatter); transposes rebalanced over three WG groups incl. the s5_gen WGs (6/14/6 tiles)
# speedup vs baseline: 1.0611x; 1.0059x over previous
.LBB0_52:
	v_writelane_b32 v253, s24, 58
	s_nop 1
	v_writelane_b32 v253, s25, 59
	s_or_b64 exec, exec, s[8:9]
	s_load_dwordx16 s[4:19], s[0:1], 0x80
	s_load_dwordx16 s[56:71], s[0:1], 0x138
	s_waitcnt lgkmcnt(0)
	v_writelane_b32 v253, s4, 60
	s_nop 1
	v_writelane_b32 v254, s8, 0
	v_writelane_b32 v254, s9, 1
	v_writelane_b32 v254, s10, 2
	v_writelane_b32 v254, s11, 3
	v_writelane_b32 v254, s12, 4
	v_writelane_b32 v254, s13, 5
	v_writelane_b32 v254, s14, 6
	v_writelane_b32 v254, s15, 7
	v_writelane_b32 v254, s16, 8
	v_writelane_b32 v253, s5, 61
	v_writelane_b32 v254, s17, 9
	v_writelane_b32 v253, s6, 62
	v_writelane_b32 v254, s18, 10
	v_writelane_b32 v253, s7, 63
	v_writelane_b32 v254, s19, 11
	s_load_dwordx16 s[4:19], s[0:1], 0xc0
	v_readlane_b32 s24, v253, 18
	v_readlane_b32 s25, v253, 19
	v_readlane_b32 s26, v253, 20
	v_readlane_b32 s27, v253, 21
	s_waitcnt lgkmcnt(0)
	v_writelane_b32 v254, s4, 12
	v_readlane_b32 s28, v253, 22
	v_readlane_b32 s29, v253, 23
	v_writelane_b32 v254, s5, 13
	v_writelane_b32 v254, s6, 14
	v_writelane_b32 v254, s7, 15
	v_writelane_b32 v254, s8, 16
	v_writelane_b32 v254, s9, 17
	v_writelane_b32 v254, s10, 18
	v_writelane_b32 v254, s11, 19
	v_writelane_b32 v254, s12, 20
	v_writelane_b32 v254, s13, 21
	v_writelane_b32 v254, s14, 22
	v_writelane_b32 v254, s15, 23
	v_writelane_b32 v254, s16, 24
	v_writelane_b32 v254, s17, 25
	v_writelane_b32 v254, s18, 26
	v_writelane_b32 v254, s19, 27
	s_mov_b64 s[4:5], s[76:77]
	s_mov_b64 s[12:13], s[84:85]
	s_mov_b64 s[6:7], s[78:79]
	s_mov_b64 s[14:15], s[86:87]
	s_mov_b64 s[10:11], s[82:83]
	s_mov_b64 s[18:19], s[90:91]
	v_readlane_b32 s30, v253, 24
	v_readlane_b32 s31, v253, 25
	v_writelane_b32 v253, s4, 42
	v_readfirstlane_b32 s0, v234
	s_lshr_b32 s0, s0, 8
	v_writelane_b32 v253, s5, 43
	v_writelane_b32 v253, s6, 44
	v_writelane_b32 v253, s7, 45
	v_writelane_b32 v253, s8, 46
	v_writelane_b32 v253, s9, 47
	v_writelane_b32 v253, s10, 48
	v_writelane_b32 v253, s11, 49
	v_writelane_b32 v253, s12, 50
	v_writelane_b32 v253, s13, 51
	v_writelane_b32 v253, s14, 52
	v_writelane_b32 v253, s15, 53
	v_writelane_b32 v253, s16, 54
	v_writelane_b32 v253, s17, 55
	s_add_i32 s40, s0, s92
	s_lshl_b32 s93, s30, 1
	v_writelane_b32 v253, s18, 56
	v_writelane_b32 v253, s19, 57
	s_movk_i32 s98, 0xc0
	s_cmpk_lt_u32 s40, 0xc0
	s_cbranch_scc1 .Ltr_go
	s_cmpk_gt_u32 s40, 0xff
	s_cbranch_scc1 .Ltr_goC
	s_add_i32 s40, s40, 0x3c0
	s_movk_i32 s98, 0x40
	s_branch .Ltr_goB
.Ltr_goC:
	s_add_i32 s40, s40, 0x700
	s_movk_i32 s98, 0x100
	s_branch .Ltr_goC2
.Ltr_go:
	s_add_u32 s74, s34, 0xfffffe50
	s_addc_u32 s75, s35, -1
	v_and_b32_e32 v20, 63, v235
	v_lshrrev_b32_e32 v21, 6, v235
	v_lshrrev_b32_e32 v112, 2, v235
	v_and_b32_e32 v113, 3, v235
	v_mul_u32_u24_e32 v1, 0x41, v21
	v_add_u32_e32 v1, v1, v20
	v_lshl_add_u32 v22, v1, 2, s72
	v_add_u32_e32 v23, 0x4200, v22
	v_mul_u32_u24_e32 v1, 0x1040, v113
	v_lshl_add_u32 v1, v112, 2, v1
	v_add_u32_e32 v24, s72, v1
	v_add_u32_e32 v25, 0x400, v24
	v_add_u32_e32 v26, 0x800, v24
	v_add_u32_e32 v27, 0xc00, v24
	v_add_u32_e32 v28, 0x4200, v24
	v_add_u32_e32 v29, 0x4200, v25
	v_add_u32_e32 v30, 0x4200, v26
	v_add_u32_e32 v31, 0x4200, v27
	v_lshlrev_b32_e32 v113, 5, v113
	s_cmpk_ge_u32 s40, 0x700
	s_cselect_b32 s0, 1, 0
	s_mul_i32 s1, s0, 0x700
	s_sub_u32 s1, s40, s1
	s_cmpk_ge_u32 s1, 0x4c0
	s_cbranch_scc1 .Ltp_c1_1
	s_movk_i32 s41, 0x50
	s_movk_i32 s42, 0xe8
	s_movk_i32 s43, 0x1210
	s_mov_b32 s44, 4
	s_movk_i32 s45, 0x880
	s_mov_b32 s46, 0x1210000
	s_mov_b32 s47, 0xa18000
	s_branch .Ltp_cj_1

.Ltp_nz_9:
	ds_write_b32 v22, v64
	ds_write_b32 v22, v65 offset:1040
	ds_write_b32 v22, v66 offset:2080
	ds_write_b32 v22, v67 offset:3120
	ds_write_b32 v22, v68 offset:4160
	ds_write_b32 v22, v69 offset:5200
	ds_write_b32 v22, v70 offset:6240
	ds_write_b32 v22, v71 offset:7280
	ds_write_b32 v22, v72 offset:8320
	ds_write_b32 v22, v73 offset:9360
	ds_write_b32 v22, v74 offset:10400
	ds_write_b32 v22, v75 offset:11440
	ds_write_b32 v22, v76 offset:12480
	ds_write_b32 v22, v77 offset:13520
	ds_write_b32 v22, v78 offset:14560
	ds_write_b32 v22, v79 offset:15600
	v_mov_b32_e32 v3, s85
	v_mad_u32_u24 v2, v112, v3, v113
	s_mov_b64 s[94:95], s[86:87]
	s_waitcnt lgkmcnt(0)
	s_barrier
	ds_read2_b32 v[4:5], v24 offset1:65
	ds_read2_b32 v[6:7], v24 offset0:130 offset1:195
	ds_read2_b32 v[8:9], v25 offset0:4 offset1:69
	ds_read2_b32 v[10:11], v25 offset0:134 offset1:199
	ds_read2_b32 v[12:13], v26 offset0:8 offset1:73
	ds_read2_b32 v[14:15], v26 offset0:138 offset1:203
	ds_read2_b32 v[16:17], v27 offset0:12 offset1:77
	ds_read2_b32 v[18:19], v27 offset0:142 offset1:207
	s_waitcnt lgkmcnt(4)
	v_cvt_pk_bf16_f32 v4, v4, v5
	v_cvt_pk_bf16_f32 v5, v6, v7
	v_cvt_pk_bf16_f32 v6, v8, v9
	v_cvt_pk_bf16_f32 v7, v10, v11
	global_store_dwordx4 v2, v[4:7], s[94:95]
	s_waitcnt lgkmcnt(0)
	v_cvt_pk_bf16_f32 v8, v12, v13
	v_cvt_pk_bf16_f32 v9, v14, v15
	v_cvt_pk_bf16_f32 v10, v16, v17
	v_cvt_pk_bf16_f32 v11, v18, v19
	global_store_dwordx4 v2, v[8:11], s[94:95] offset:16
	s_waitcnt vmcnt(38)
	s_cmpk_ge_i32 s88, 0x40
	s_cbranch_scc1 .Ltp_nz_10
	v_cmp_gt_i32_e32 vcc, s88, v20
	v_cndmask_b32_e32 v96, 0, v96, vcc
	v_cndmask_b32_e32 v97, 0, v97, vcc
	v_cndmask_b32_e32 v98, 0, v98, vcc
	v_cndmask_b32_e32 v99, 0, v99, vcc
	v_cndmask_b32_e32 v100, 0, v100, vcc
	v_cndmask_b32_e32 v101, 0, v101, vcc
	v_cndmask_b32_e32 v102, 0, v102, vcc
	v_cndmask_b32_e32 v103, 0, v103, vcc
	v_cndmask_b32_e32 v104, 0, v104, vcc
	v_cndmask_b32_e32 v105, 0, v105, vcc
	v_cndmask_b32_e32 v106, 0, v106, vcc
	v_cndmask_b32_e32 v107, 0, v107, vcc
	v_cndmask_b32_e32 v108, 0, v108, vcc
	v_cndmask_b32_e32 v109, 0, v109, vcc
	v_cndmask_b32_e32 v110, 0, v110, vcc
	v_cndmask_b32_e32 v111, 0, v111, vcc
.Ltp_nz_10:
	ds_write_b32 v23, v96
	ds_write_b32 v23, v97 offset:1040
	ds_write_b32 v23, v98 offset:2080
	ds_write_b32 v23, v99 offset:3120
	ds_write_b32 v23, v100 offset:4160
	ds_write_b32 v23, v101 offset:5200
	ds_write_b32 v23, v102 offset:6240
	ds_write_b32 v23, v103 offset:7280
	ds_write_b32 v23, v104 offset:8320
	ds_write_b32 v23, v105 offset:9360
	ds_write_b32 v23, v106 offset:10400
	ds_write_b32 v23, v107 offset:11440
	ds_write_b32 v23, v108 offset:12480
	ds_write_b32 v23, v109 offset:13520
	ds_write_b32 v23, v110 offset:14560
	ds_write_b32 v23, v111 offset:15600
	v_mov_b32_e32 v3, s89
	v_mad_u32_u24 v2, v112, v3, v113
	s_mov_b64 s[94:95], s[90:91]
	s_waitcnt lgkmcnt(0)
	s_barrier
	ds_read2_b32 v[4:5], v28 offset1:65
	ds_read2_b32 v[6:7], v28 offset0:130 offset1:195
	ds_read2_b32 v[8:9], v29 offset0:4 offset1:69
	ds_read2_b32 v[10:11], v29 offset0:134 offset1:199
	ds_read2_b32 v[12:13], v30 offset0:8 offset1:73
	ds_read2_b32 v[14:15], v30 offset0:138 offset1:203
	ds_read2_b32 v[16:17], v31 offset0:12 offset1:77
	ds_read2_b32 v[18:19], v31 offset0:142 offset1:207
	s_waitcnt lgkmcnt(4)
	v_cvt_pk_bf16_f32 v4, v4, v5
	v_cvt_pk_bf16_f32 v5, v6, v7
	v_cvt_pk_bf16_f32 v6, v8, v9
	v_cvt_pk_bf16_f32 v7, v10, v11
	global_store_dwordx4 v2, v[4:7], s[94:95]
	s_waitcnt lgkmcnt(0)
	v_cvt_pk_bf16_f32 v8, v12, v13
	v_cvt_pk_bf16_f32 v9, v14, v15
	v_cvt_pk_bf16_f32 v10, v16, v17
	v_cvt_pk_bf16_f32 v11, v18, v19
	global_store_dwordx4 v2, v[8:11], s[94:95] offset:16
	s_waitcnt vmcnt(24)
	s_cmpk_ge_i32 s76, 0x40
	s_cbranch_scc1 .Ltp_nz_11
	v_cmp_gt_i32_e32 vcc, s76, v20
	v_cndmask_b32_e32 v32, 0, v32, vcc
	v_cndmask_b32_e32 v33, 0, v33, vcc
	v_cndmask_b32_e32 v34, 0, v34, vcc
	v_cndmask_b32_e32 v35, 0, v35, vcc
	v_cndmask_b32_e32 v36, 0, v36, vcc
	v_cndmask_b32_e32 v37, 0, v37, vcc
	v_cndmask_b32_e32 v38, 0, v38, vcc
	v_cndmask_b32_e32 v39, 0, v39, vcc
	v_cndmask_b32_e32 v40, 0, v40, vcc
	v_cndmask_b32_e32 v41, 0, v41, vcc
	v_cndmask_b32_e32 v42, 0, v42, vcc
	v_cndmask_b32_e32 v43, 0, v43, vcc
	v_cndmask_b32_e32 v44, 0, v44, vcc
	v_cndmask_b32_e32 v45, 0, v45, vcc
	v_cndmask_b32_e32 v46, 0, v46, vcc
	v_cndmask_b32_e32 v47, 0, v47, vcc
.Ltp_nz_11:
	ds_write_b32 v22, v32
	ds_write_b32 v22, v33 offset:1040
	ds_write_b32 v22, v34 offset:2080
	ds_write_b32 v22, v35 offset:3120
	ds_write_b32 v22, v36 offset:4160
	ds_write_b32 v22, v37 offset:5200
	ds_write_b32 v22, v38 offset:6240
	ds_write_b32 v22, v39 offset:7280
	ds_write_b32 v22, v40 offset:8320
	ds_write_b32 v22, v41 offset:9360
	ds_write_b32 v22, v42 offset:10400
	ds_write_b32 v22, v43 offset:11440
	ds_write_b32 v22, v44 offset:12480
	ds_write_b32 v22, v45 offset:13520
	ds_write_b32 v22, v46 offset:14560
	ds_write_b32 v22, v47 offset:15600
	v_mov_b32_e32 v3, s77
	v_mad_u32_u24 v2, v112, v3, v113
	s_mov_b64 s[94:95], s[78:79]
	s_waitcnt lgkmcnt(0)
	s_barrier
	ds_read2_b32 v[4:5], v24 offset1:65
	ds_read2_b32 v[6:7], v24 offset0:130 offset1:195
	ds_read2_b32 v[8:9], v25 offset0:4 offset1:69
	ds_read2_b32 v[10:11], v25 offset0:134 offset1:199
	ds_read2_b32 v[12:13], v26 offset0:8 offset1:73
	ds_read2_b32 v[14:15], v26 offset0:138 offset1:203
	ds_read2_b32 v[16:17], v27 offset0:12 offset1:77
	ds_read2_b32 v[18:19], v27 offset0:142 offset1:207
	s_waitcnt lgkmcnt(4)
	v_cvt_pk_bf16_f32 v4, v4, v5
	v_cvt_pk_bf16_f32 v5, v6, v7
	v_cvt_pk_bf16_f32 v6, v8, v9
	v_cvt_pk_bf16_f32 v7, v10, v11
	global_store_dwordx4 v2, v[4:7], s[94:95]
	s_waitcnt lgkmcnt(0)
	v_cvt_pk_bf16_f32 v8, v12, v13
	v_cvt_pk_bf16_f32 v9, v14, v15
	v_cvt_pk_bf16_f32 v10, v16, v17
	v_cvt_pk_bf16_f32 v11, v18, v19
	global_store_dwordx4 v2, v[8:11], s[94:95] offset:16
	s_waitcnt vmcnt(8)
	s_cmpk_ge_i32 s80, 0x40
	s_cbranch_scc1 .Ltp_nz_12
	v_cmp_gt_i32_e32 vcc, s80, v20
	v_cndmask_b32_e32 v48, 0, v48, vcc
	v_cndmask_b32_e32 v49, 0, v49, vcc
	v_cndmask_b32_e32 v50, 0, v50, vcc
	v_cndmask_b32_e32 v51, 0, v51, vcc
	v_cndmask_b32_e32 v52, 0, v52, vcc
	v_cndmask_b32_e32 v53, 0, v53, vcc
	v_cndmask_b32_e32 v54, 0, v54, vcc
	v_cndmask_b32_e32 v55, 0, v55, vcc
	v_cndmask_b32_e32 v56, 0, v56, vcc
	v_cndmask_b32_e32 v57, 0, v57, vcc
	v_cndmask_b32_e32 v58, 0, v58, vcc
	v_cndmask_b32_e32 v59, 0, v59, vcc
	v_cndmask_b32_e32 v60, 0, v60, vcc
	v_cndmask_b32_e32 v61, 0, v61, vcc
	v_cndmask_b32_e32 v62, 0, v62, vcc
	v_cndmask_b32_e32 v63, 0, v63, vcc
.Ltp_nz_12:
	ds_write_b32 v23, v48
	ds_write_b32 v23, v49 offset:1040
	ds_write_b32 v23, v50 offset:2080
	ds_write_b32 v23, v51 offset:3120
	ds_write_b32 v23, v52 offset:4160
	ds_write_b32 v23, v53 offset:5200
	ds_write_b32 v23, v54 offset:6240
	ds_write_b32 v23, v55 offset:7280
	ds_write_b32 v23, v56 offset:8320
	ds_write_b32 v23, v57 offset:9360
	ds_write_b32 v23, v58 offset:10400
	ds_write_b32 v23, v59 offset:11440
	ds_write_b32 v23, v60 offset:12480
	ds_write_b32 v23, v61 offset:13520
	ds_write_b32 v23, v62 offset:14560
	ds_write_b32 v23, v63 offset:15600
	v_mov_b32_e32 v3, s81
	v_mad_u32_u24 v2, v112, v3, v113
	s_mov_b64 s[94:95], s[82:83]
	s_waitcnt lgkmcnt(0)
	s_barrier
	ds_read2_b32 v[4:5], v28 offset1:65
	ds_read2_b32 v[6:7], v28 offset0:130 offset1:195
	ds_read2_b32 v[8:9], v29 offset0:4 offset1:69
	ds_read2_b32 v[10:11], v29 offset0:134 offset1:199
	ds_read2_b32 v[12:13], v30 offset0:8 offset1:73
	ds_read2_b32 v[14:15], v30 offset0:138 offset1:203
	ds_read2_b32 v[16:17], v31 offset0:12 offset1:77
	ds_read2_b32 v[18:19], v31 offset0:142 offset1:207
	s_waitcnt lgkmcnt(4)
	v_cvt_pk_bf16_f32 v4, v4, v5
	v_cvt_pk_bf16_f32 v5, v6, v7
	v_cvt_pk_bf16_f32 v6, v8, v9
	v_cvt_pk_bf16_f32 v7, v10, v11
	global_store_dwordx4 v2, v[4:7], s[94:95]
	s_waitcnt lgkmcnt(0)
	v_cvt_pk_bf16_f32 v8, v12, v13
	v_cvt_pk_bf16_f32 v9, v14, v15
	v_cvt_pk_bf16_f32 v10, v16, v17
	v_cvt_pk_bf16_f32 v11, v18, v19
	global_store_dwordx4 v2, v[8:11], s[94:95] offset:16
	s_branch .Ltp_done

.Ltp_cj_24:
	s_load_dwordx2 s[48:49], s[74:75], s41
	s_load_dwordx2 s[50:51], s[74:75], s42
	s_lshr_b32 s52, s1, s44
	s_lshl_b32 s53, s52, s44
	s_sub_u32 s53, s1, s53
	s_lshl_b32 s52, s52, 6
	s_lshl_b32 s53, s53, 6
	s_sub_i32 s88, s43, s52
	s_mov_b32 s89, s45
	s_mul_i32 s54, s0, s46
	s_mul_i32 s55, s53, s43
	s_lshl_b32 s55, s55, 2
	s_add_u32 s54, s54, s55
	s_mul_i32 s55, s0, s47
	s_mul_i32 s41, s52, s45
	s_add_u32 s55, s55, s41
	s_lshl_b32 s41, s53, 1
	s_add_u32 s55, s55, s41
	s_add_i32 s41, s43, -1
	v_add_u32_e32 v3, s52, v20
	v_min_u32_e32 v3, s41, v3
	s_lshl_b32 s42, s43, 2
	v_mul_u32_u24_e32 v1, s42, v21
	v_lshl_add_u32 v1, v3, 2, v1
	s_lshl_b32 s42, s43, 4
	s_add_i32 s40, s40, s98
	s_waitcnt lgkmcnt(0)
	s_add_u32 s4, s48, s54
	s_addc_u32 s5, s49, 0
	s_add_u32 s90, s50, s55
	s_addc_u32 s91, s51, 0
	s_add_u32 s6, s4, s42
	s_addc_u32 s7, s5, 0
	s_add_u32 s8, s6, s42
	s_addc_u32 s9, s7, 0
	s_add_u32 s10, s8, s42
	s_addc_u32 s11, s9, 0
	s_add_u32 s12, s10, s42
	s_addc_u32 s13, s11, 0
	s_add_u32 s14, s12, s42
	s_addc_u32 s15, s13, 0
	s_add_u32 s16, s14, s42
	s_addc_u32 s17, s15, 0
	s_add_u32 s18, s16, s42
	s_addc_u32 s19, s17, 0
	s_add_u32 s20, s18, s42
	s_addc_u32 s21, s19, 0
	s_add_u32 s22, s20, s42
	s_addc_u32 s23, s21, 0
	s_add_u32 s24, s22, s42
	s_addc_u32 s25, s23, 0
	s_add_u32 s26, s24, s42
	s_addc_u32 s27, s25, 0
	s_add_u32 s28, s26, s42
	s_addc_u32 s29, s27, 0
	s_add_u32 s30, s28, s42
	s_addc_u32 s31, s29, 0
	s_add_u32 s36, s30, s42
	s_addc_u32 s37, s31, 0
	s_add_u32 s38, s36, s42
	s_addc_u32 s39, s37, 0
	s_nop 4
	global_load_dword v96, v1, s[4:5] nt
	global_load_dword v97, v1, s[6:7] nt
	global_load_dword v98, v1, s[8:9] nt
	global_load_dword v99, v1, s[10:11] nt
	global_load_dword v100, v1, s[12:13] nt
	global_load_dword v101, v1, s[14:15] nt
	global_load_dword v102, v1, s[16:17] nt
	global_load_dword v103, v1, s[18:19] nt
	global_load_dword v104, v1, s[20:21] nt
	global_load_dword v105, v1, s[22:23] nt
	global_load_dword v106, v1, s[24:25] nt
	global_load_dword v107, v1, s[26:27] nt
	global_load_dword v108, v1, s[28:29] nt
	global_load_dword v109, v1, s[30:31] nt
	global_load_dword v110, v1, s[36:37] nt
	global_load_dword v111, v1, s[38:39] nt
	s_waitcnt lgkmcnt(0)
	s_barrier
	ds_read2_b32 v[4:5], v28 offset1:65
	ds_read2_b32 v[6:7], v28 offset0:130 offset1:195
	ds_read2_b32 v[8:9], v29 offset0:4 offset1:69
	ds_read2_b32 v[10:11], v29 offset0:134 offset1:199
	ds_read2_b32 v[12:13], v30 offset0:8 offset1:73
	ds_read2_b32 v[14:15], v30 offset0:138 offset1:203
	ds_read2_b32 v[16:17], v31 offset0:12 offset1:77
	ds_read2_b32 v[18:19], v31 offset0:142 offset1:207
	s_waitcnt lgkmcnt(4)
	v_cvt_pk_bf16_f32 v4, v4, v5
	v_cvt_pk_bf16_f32 v5, v6, v7
	v_cvt_pk_bf16_f32 v6, v8, v9
	v_cvt_pk_bf16_f32 v7, v10, v11
	global_store_dwordx4 v2, v[4:7], s[94:95]
	s_waitcnt lgkmcnt(0)
	v_cvt_pk_bf16_f32 v8, v12, v13
	v_cvt_pk_bf16_f32 v9, v14, v15
	v_cvt_pk_bf16_f32 v10, v16, v17
	v_cvt_pk_bf16_f32 v11, v18, v19
	global_store_dwordx4 v2, v[8:11], s[94:95] offset:16
	s_waitcnt vmcnt(56)
	s_cmpk_ge_i32 s76, 0x40
	s_cbranch_scc1 .Ltp_nz_25
	v_cmp_gt_i32_e32 vcc, s76, v20
	v_cndmask_b32_e32 v32, 0, v32, vcc
	v_cndmask_b32_e32 v33, 0, v33, vcc
	v_cndmask_b32_e32 v34, 0, v34, vcc
	v_cndmask_b32_e32 v35, 0, v35, vcc
	v_cndmask_b32_e32 v36, 0, v36, vcc
	v_cndmask_b32_e32 v37, 0, v37, vcc
	v_cndmask_b32_e32 v38, 0, v38, vcc
	v_cndmask_b32_e32 v39, 0, v39, vcc
	v_cndmask_b32_e32 v40, 0, v40, vcc
	v_cndmask_b32_e32 v41, 0, v41, vcc
	v_cndmask_b32_e32 v42, 0, v42, vcc
	v_cndmask_b32_e32 v43, 0, v43, vcc
	v_cndmask_b32_e32 v44, 0, v44, vcc
	v_cndmask_b32_e32 v45, 0, v45, vcc
	v_cndmask_b32_e32 v46, 0, v46, vcc
	v_cndmask_b32_e32 v47, 0, v47, vcc

.Ltp_nz_37:
	ds_write_b32 v22, v64
	ds_write_b32 v22, v65 offset:1040
	ds_write_b32 v22, v66 offset:2080
	ds_write_b32 v22, v67 offset:3120
	ds_write_b32 v22, v68 offset:4160
	ds_write_b32 v22, v69 offset:5200
	ds_write_b32 v22, v70 offset:6240
	ds_write_b32 v22, v71 offset:7280
	ds_write_b32 v22, v72 offset:8320
	ds_write_b32 v22, v73 offset:9360
	ds_write_b32 v22, v74 offset:10400
	ds_write_b32 v22, v75 offset:11440
	ds_write_b32 v22, v76 offset:12480
	ds_write_b32 v22, v77 offset:13520
	ds_write_b32 v22, v78 offset:14560
	ds_write_b32 v22, v79 offset:15600
	v_mov_b32_e32 v3, s85
	v_mad_u32_u24 v2, v112, v3, v113
	s_mov_b64 s[94:95], s[86:87]
	s_waitcnt lgkmcnt(0)
	s_barrier
	ds_read2_b32 v[4:5], v24 offset1:65
	ds_read2_b32 v[6:7], v24 offset0:130 offset1:195
	ds_read2_b32 v[8:9], v25 offset0:4 offset1:69
	ds_read2_b32 v[10:11], v25 offset0:134 offset1:199
	ds_read2_b32 v[12:13], v26 offset0:8 offset1:73
	ds_read2_b32 v[14:15], v26 offset0:138 offset1:203
	ds_read2_b32 v[16:17], v27 offset0:12 offset1:77
	ds_read2_b32 v[18:19], v27 offset0:142 offset1:207
	s_waitcnt lgkmcnt(4)
	v_cvt_pk_bf16_f32 v4, v4, v5
	v_cvt_pk_bf16_f32 v5, v6, v7
	v_cvt_pk_bf16_f32 v6, v8, v9
	v_cvt_pk_bf16_f32 v7, v10, v11
	global_store_dwordx4 v2, v[4:7], s[94:95]
	s_waitcnt lgkmcnt(0)
	v_cvt_pk_bf16_f32 v8, v12, v13
	v_cvt_pk_bf16_f32 v9, v14, v15
	v_cvt_pk_bf16_f32 v10, v16, v17
	v_cvt_pk_bf16_f32 v11, v18, v19
	global_store_dwordx4 v2, v[8:11], s[94:95] offset:16
	s_waitcnt vmcnt(40)
	s_cmpk_ge_i32 s88, 0x40
	s_cbranch_scc1 .Ltp_nz_38
	v_cmp_gt_i32_e32 vcc, s88, v20
	v_cndmask_b32_e32 v96, 0, v96, vcc
	v_cndmask_b32_e32 v97, 0, v97, vcc
	v_cndmask_b32_e32 v98, 0, v98, vcc
	v_cndmask_b32_e32 v99, 0, v99, vcc
	v_cndmask_b32_e32 v100, 0, v100, vcc
	v_cndmask_b32_e32 v101, 0, v101, vcc
	v_cndmask_b32_e32 v102, 0, v102, vcc
	v_cndmask_b32_e32 v103, 0, v103, vcc
	v_cndmask_b32_e32 v104, 0, v104, vcc
	v_cndmask_b32_e32 v105, 0, v105, vcc
	v_cndmask_b32_e32 v106, 0, v106, vcc
	v_cndmask_b32_e32 v107, 0, v107, vcc
	v_cndmask_b32_e32 v108, 0, v108, vcc
	v_cndmask_b32_e32 v109, 0, v109, vcc
	v_cndmask_b32_e32 v110, 0, v110, vcc
	v_cndmask_b32_e32 v111, 0, v111, vcc

.Ltp_nz_52:
	ds_write_b32 v23, v48
	ds_write_b32 v23, v49 offset:1040
	ds_write_b32 v23, v50 offset:2080
	ds_write_b32 v23, v51 offset:3120
	ds_write_b32 v23, v52 offset:4160
	ds_write_b32 v23, v53 offset:5200
	ds_write_b32 v23, v54 offset:6240
	ds_write_b32 v23, v55 offset:7280
	ds_write_b32 v23, v56 offset:8320
	ds_write_b32 v23, v57 offset:9360
	ds_write_b32 v23, v58 offset:10400
	ds_write_b32 v23, v59 offset:11440
	ds_write_b32 v23, v60 offset:12480
	ds_write_b32 v23, v61 offset:13520
	ds_write_b32 v23, v62 offset:14560
	ds_write_b32 v23, v63 offset:15600
	v_mov_b32_e32 v3, s81
	v_mad_u32_u24 v2, v112, v3, v113
	s_mov_b64 s[94:95], s[82:83]
	s_waitcnt lgkmcnt(0)
	s_barrier
	ds_read2_b32 v[4:5], v28 offset1:65
	ds_read2_b32 v[6:7], v28 offset0:130 offset1:195
	ds_read2_b32 v[8:9], v29 offset0:4 offset1:69
	ds_read2_b32 v[10:11], v29 offset0:134 offset1:199
	ds_read2_b32 v[12:13], v30 offset0:8 offset1:73
	ds_read2_b32 v[14:15], v30 offset0:138 offset1:203
	ds_read2_b32 v[16:17], v31 offset0:12 offset1:77
	ds_read2_b32 v[18:19], v31 offset0:142 offset1:207
	s_waitcnt lgkmcnt(4)
	v_cvt_pk_bf16_f32 v4, v4, v5
	v_cvt_pk_bf16_f32 v5, v6, v7
	v_cvt_pk_bf16_f32 v6, v8, v9
	v_cvt_pk_bf16_f32 v7, v10, v11
	global_store_dwordx4 v2, v[4:7], s[94:95]
	s_waitcnt lgkmcnt(0)
	v_cvt_pk_bf16_f32 v8, v12, v13
	v_cvt_pk_bf16_f32 v9, v14, v15
	v_cvt_pk_bf16_f32 v10, v16, v17
	v_cvt_pk_bf16_f32 v11, v18, v19
	global_store_dwordx4 v2, v[8:11], s[94:95] offset:16
.Ltp_done:
	s_waitcnt lgkmcnt(0)
	s_barrier
.LBB0_103:
	v_readlane_b32 s76, v253, 42
	v_readlane_b32 s24, v253, 18
	v_readlane_b32 s78, v253, 44
	v_readlane_b32 s79, v253, 45
	v_readlane_b32 s26, v253, 20
	v_readlane_b32 s27, v253, 21
	v_readlane_b32 s28, v253, 22
	v_readlane_b32 s29, v253, 23
	v_readlane_b32 s30, v253, 24
	v_readlane_b32 s31, v253, 25
	v_readlane_b32 s77, v253, 43
	v_readlane_b32 s80, v253, 46
	v_readlane_b32 s81, v253, 47
	v_readlane_b32 s82, v253, 48
	v_readlane_b32 s83, v253, 49
	v_readlane_b32 s84, v253, 50
	v_readlane_b32 s85, v253, 51
	v_readlane_b32 s86, v253, 52
	v_readlane_b32 s87, v253, 53
	v_readlane_b32 s88, v253, 54
	v_readlane_b32 s89, v253, 55
	v_readlane_b32 s90, v253, 56
	v_readlane_b32 s91, v253, 57
	v_readlane_b32 s25, v253, 19

.LBB0_128:
	s_or_b64 exec, exec, s[12:13]
	s_lshl_b64 s[0:1], s[10:11], 18
	v_readlane_b32 s72, v253, 8
	v_readlane_b32 s73, v253, 9
	s_add_u32 s0, s72, s0
	s_addc_u32 s1, s73, s1
	v_and_b32_e32 v2, 3, v18
	s_lshl_b32 s4, s38, 7
	v_lshl_or_b32 v10, v2, 5, s4
	v_lshlrev_b32_e32 v8, 6, v2
	s_lshl_b32 s6, s38, 6
	v_lshl_add_u64 v[2:3], s[0:1], 0, v[10:11]
	s_mov_b32 s4, 0
	v_readlane_b32 s74, v253, 10
	v_readlane_b32 s75, v253, 11
	v_readlane_b32 s76, v253, 12
	v_readlane_b32 s77, v253, 13
	v_readlane_b32 s78, v253, 14
	v_readlane_b32 s79, v253, 15
	s_waitcnt lgkmcnt(0)
	s_barrier
	v_lshrrev_b32_e32 v4, 2, v18
	v_or_b32_e32 v5, v8, v4
	v_lshl_add_u32 v76, v5, 3, s41
	v_lshl_add_u32 v77, v4, 6, s41
	v_subrev_u32_e32 v9, s0, v2
	v_lshl_add_u32 v72, v4, 10, v9
	v_add_u32_e32 v73, 0x10000, v72
	v_add_u32_e32 v74, 0x20000, v72
	v_add_u32_e32 v75, 0x30000, v72
	ds_read_b64 v[36:37], v76 offset:28672
	ds_read_b128 v[40:43], v77 offset:0
	ds_read_b128 v[44:47], v77 offset:16
	ds_read_b128 v[48:51], v77 offset:32
	ds_read_b128 v[52:55], v77 offset:48
	ds_read_b128 v[56:59], v77 offset:8192
	ds_read_b128 v[60:63], v77 offset:8208
	ds_read_b128 v[64:67], v77 offset:8224
	ds_read_b128 v[68:71], v77 offset:8240
	s_waitcnt lgkmcnt(0)
	v_mul_f32_e32 v4, v36, v40
	v_mul_f32_e32 v5, v37, v56
	v_sub_f32_e32 v19, v4, v5
	v_mul_f32_e32 v4, v36, v41
	v_mul_f32_e32 v5, v37, v57
	v_sub_f32_e32 v20, v4, v5
	v_mul_f32_e32 v4, v36, v42
	v_mul_f32_e32 v5, v37, v58
	v_sub_f32_e32 v21, v4, v5
	v_mul_f32_e32 v4, v36, v43
	v_mul_f32_e32 v5, v37, v59
	v_sub_f32_e32 v22, v4, v5
	v_mul_f32_e32 v4, v36, v44
	v_mul_f32_e32 v5, v37, v60
	v_sub_f32_e32 v23, v4, v5
	v_mul_f32_e32 v4, v36, v45
	v_mul_f32_e32 v5, v37, v61
	v_sub_f32_e32 v24, v4, v5
	v_mul_f32_e32 v4, v36, v46
	v_mul_f32_e32 v5, v37, v62
	v_sub_f32_e32 v25, v4, v5
	v_mul_f32_e32 v4, v36, v47
	v_mul_f32_e32 v5, v37, v63
	v_sub_f32_e32 v26, v4, v5
	v_mul_f32_e32 v4, v36, v48
	v_mul_f32_e32 v5, v37, v64
	v_sub_f32_e32 v27, v4, v5
	v_mul_f32_e32 v4, v36, v49
	v_mul_f32_e32 v5, v37, v65
	v_sub_f32_e32 v28, v4, v5
	v_mul_f32_e32 v4, v36, v50
	v_mul_f32_e32 v5, v37, v66
	v_sub_f32_e32 v29, v4, v5
	v_mul_f32_e32 v4, v36, v51
	v_mul_f32_e32 v5, v37, v67
	v_sub_f32_e32 v30, v4, v5
	v_mul_f32_e32 v4, v36, v52
	v_mul_f32_e32 v5, v37, v68
	v_sub_f32_e32 v31, v4, v5
	v_mul_f32_e32 v4, v36, v53
	v_mul_f32_e32 v5, v37, v69
	v_sub_f32_e32 v32, v4, v5
	v_mul_f32_e32 v4, v36, v54
	v_mul_f32_e32 v5, v37, v70
	v_sub_f32_e32 v33, v4, v5
	v_mul_f32_e32 v4, v36, v55
	v_mul_f32_e32 v5, v37, v71
	v_sub_f32_e32 v34, v4, v5
	v_cvt_pk_bf16_f32 v84, v19, v20
	v_cvt_pk_bf16_f32 v85, v21, v22
	v_cvt_pk_bf16_f32 v86, v23, v24
	v_cvt_pk_bf16_f32 v87, v25, v26
	v_cvt_pk_bf16_f32 v88, v27, v28
	v_cvt_pk_bf16_f32 v89, v29, v30
	v_cvt_pk_bf16_f32 v90, v31, v32
	v_cvt_pk_bf16_f32 v91, v33, v34
	global_store_dwordx4 v72, v[84:87], s[0:1]
	global_store_dwordx4 v72, v[88:91], s[0:1] offset:16
	v_mul_f32_e32 v4, v36, v56
	v_mul_f32_e32 v5, v37, v40
	v_add_f32_e32 v19, v4, v5
	v_mul_f32_e32 v4, v36, v57
	v_mul_f32_e32 v5, v37, v41
	v_add_f32_e32 v20, v4, v5
	v_mul_f32_e32 v4, v36, v58
	v_mul_f32_e32 v5, v37, v42
	v_add_f32_e32 v21, v4, v5
	v_mul_f32_e32 v4, v36, v59
	v_mul_f32_e32 v5, v37, v43
	v_add_f32_e32 v22, v4, v5
	v_mul_f32_e32 v4, v36, v60
	v_mul_f32_e32 v5, v37, v44
	v_add_f32_e32 v23, v4, v5
	v_mul_f32_e32 v4, v36, v61
	v_mul_f32_e32 v5, v37, v45
	v_add_f32_e32 v24, v4, v5
	v_mul_f32_e32 v4, v36, v62
	v_mul_f32_e32 v5, v37, v46
	v_add_f32_e32 v25, v4, v5
	v_mul_f32_e32 v4, v36, v63
	v_mul_f32_e32 v5, v37, v47
	v_add_f32_e32 v26, v4, v5
	v_mul_f32_e32 v4, v36, v64
	v_mul_f32_e32 v5, v37, v48
	v_add_f32_e32 v27, v4, v5
	v_mul_f32_e32 v4, v36, v65
	v_mul_f32_e32 v5, v37, v49
	v_add_f32_e32 v28, v4, v5
	v_mul_f32_e32 v4, v36, v66
	v_mul_f32_e32 v5, v37, v50
	v_add_f32_e32 v29, v4, v5
	v_mul_f32_e32 v4, v36, v67
	v_mul_f32_e32 v5, v37, v51
	v_add_f32_e32 v30, v4, v5
	v_mul_f32_e32 v4, v36, v68
	v_mul_f32_e32 v5, v37, v52
	v_add_f32_e32 v31, v4, v5
	v_mul_f32_e32 v4, v36, v69
	v_mul_f32_e32 v5, v37, v53
	v_add_f32_e32 v32, v4, v5
	v_mul_f32_e32 v4, v36, v70
	v_mul_f32_e32 v5, v37, v54
	v_add_f32_e32 v33, v4, v5
	v_mul_f32_e32 v4, v36, v71
	v_mul_f32_e32 v5, v37, v55
	v_add_f32_e32 v34, v4, v5
	v_cvt_pk_bf16_f32 v92, v19, v20
	v_cvt_pk_bf16_f32 v93, v21, v22
	v_cvt_pk_bf16_f32 v94, v23, v24
	v_cvt_pk_bf16_f32 v95, v25, v26
	v_cvt_pk_bf16_f32 v96, v27, v28
	v_cvt_pk_bf16_f32 v97, v29, v30
	v_cvt_pk_bf16_f32 v98, v31, v32
	v_cvt_pk_bf16_f32 v99, v33, v34
	global_store_dwordx4 v73, v[92:95], s[0:1]
	global_store_dwordx4 v73, v[96:99], s[0:1] offset:16
	ds_read_b64 v[36:37], v76 offset:30720
	ds_read_b128 v[40:43], v77 offset:4096
	ds_read_b128 v[44:47], v77 offset:4112
	ds_read_b128 v[48:51], v77 offset:4128
	ds_read_b128 v[52:55], v77 offset:4144
	ds_read_b128 v[56:59], v77 offset:12288
	ds_read_b128 v[60:63], v77 offset:12304
	ds_read_b128 v[64:67], v77 offset:12320
	ds_read_b128 v[68:71], v77 offset:12336
	s_waitcnt lgkmcnt(0)
	v_mul_f32_e32 v4, v36, v40
	v_mul_f32_e32 v5, v37, v56
	v_sub_f32_e32 v19, v4, v5
	v_mul_f32_e32 v4, v36, v41
	v_mul_f32_e32 v5, v37, v57
	v_sub_f32_e32 v20, v4, v5
	v_mul_f32_e32 v4, v36, v42
	v_mul_f32_e32 v5, v37, v58
	v_sub_f32_e32 v21, v4, v5
	v_mul_f32_e32 v4, v36, v43
	v_mul_f32_e32 v5, v37, v59
	v_sub_f32_e32 v22, v4, v5
	v_mul_f32_e32 v4, v36, v44
	v_mul_f32_e32 v5, v37, v60
	v_sub_f32_e32 v23, v4, v5
	v_mul_f32_e32 v4, v36, v45
	v_mul_f32_e32 v5, v37, v61
	v_sub_f32_e32 v24, v4, v5
	v_mul_f32_e32 v4, v36, v46
	v_mul_f32_e32 v5, v37, v62
	v_sub_f32_e32 v25, v4, v5
	v_mul_f32_e32 v4, v36, v47
	v_mul_f32_e32 v5, v37, v63
	v_sub_f32_e32 v26, v4, v5
	v_mul_f32_e32 v4, v36, v48
	v_mul_f32_e32 v5, v37, v64
	v_sub_f32_e32 v27, v4, v5
	v_mul_f32_e32 v4, v36, v49
	v_mul_f32_e32 v5, v37, v65
	v_sub_f32_e32 v28, v4, v5
	v_mul_f32_e32 v4, v36, v50
	v_mul_f32_e32 v5, v37, v66
	v_sub_f32_e32 v29, v4, v5
	v_mul_f32_e32 v4, v36, v51
	v_mul_f32_e32 v5, v37, v67
	v_sub_f32_e32 v30, v4, v5
	v_mul_f32_e32 v4, v36, v52
	v_mul_f32_e32 v5, v37, v68
	v_sub_f32_e32 v31, v4, v5
	v_mul_f32_e32 v4, v36, v53
	v_mul_f32_e32 v5, v37, v69
	v_sub_f32_e32 v32, v4, v5
	v_mul_f32_e32 v4, v36, v54
	v_mul_f32_e32 v5, v37, v70
	v_sub_f32_e32 v33, v4, v5
	v_mul_f32_e32 v4, v36, v55
	v_mul_f32_e32 v5, v37, v71
	v_sub_f32_e32 v34, v4, v5
	v_cvt_pk_bf16_f32 v84, v19, v20
	v_cvt_pk_bf16_f32 v85, v21, v22
	v_cvt_pk_bf16_f32 v86, v23, v24
	v_cvt_pk_bf16_f32 v87, v25, v26
	v_cvt_pk_bf16_f32 v88, v27, v28
	v_cvt_pk_bf16_f32 v89, v29, v30
	v_cvt_pk_bf16_f32 v90, v31, v32
	v_cvt_pk_bf16_f32 v91, v33, v34
	global_store_dwordx4 v74, v[84:87], s[0:1]
	global_store_dwordx4 v74, v[88:91], s[0:1] offset:16
	v_mul_f32_e32 v4, v36, v56
	v_mul_f32_e32 v5, v37, v40
	v_add_f32_e32 v19, v4, v5
	v_mul_f32_e32 v4, v36, v57
	v_mul_f32_e32 v5, v37, v41
	v_add_f32_e32 v20, v4, v5
	v_mul_f32_e32 v4, v36, v58
	v_mul_f32_e32 v5, v37, v42
	v_add_f32_e32 v21, v4, v5
	v_mul_f32_e32 v4, v36, v59
	v_mul_f32_e32 v5, v37, v43
	v_add_f32_e32 v22, v4, v5
	v_mul_f32_e32 v4, v36, v60
	v_mul_f32_e32 v5, v37, v44
	v_add_f32_e32 v23, v4, v5
	v_mul_f32_e32 v4, v36, v61
	v_mul_f32_e32 v5, v37, v45
	v_add_f32_e32 v24, v4, v5
	v_mul_f32_e32 v4, v36, v62
	v_mul_f32_e32 v5, v37, v46
	v_add_f32_e32 v25, v4, v5
	v_mul_f32_e32 v4, v36, v63
	v_mul_f32_e32 v5, v37, v47
	v_add_f32_e32 v26, v4, v5
	v_mul_f32_e32 v4, v36, v64
	v_mul_f32_e32 v5, v37, v48
	v_add_f32_e32 v27, v4, v5
	v_mul_f32_e32 v4, v36, v65
	v_mul_f32_e32 v5, v37, v49
	v_add_f32_e32 v28, v4, v5
	v_mul_f32_e32 v4, v36, v66
	v_mul_f32_e32 v5, v37, v50
	v_add_f32_e32 v29, v4, v5
	v_mul_f32_e32 v4, v36, v67
	v_mul_f32_e32 v5, v37, v51
	v_add_f32_e32 v30, v4, v5
	v_mul_f32_e32 v4, v36, v68
	v_mul_f32_e32 v5, v37, v52
	v_add_f32_e32 v31, v4, v5
	v_mul_f32_e32 v4, v36, v69
	v_mul_f32_e32 v5, v37, v53
	v_add_f32_e32 v32, v4, v5
	v_mul_f32_e32 v4, v36, v70
	v_mul_f32_e32 v5, v37, v54
	v_add_f32_e32 v33, v4, v5
	v_mul_f32_e32 v4, v36, v71
	v_mul_f32_e32 v5, v37, v55
	v_add_f32_e32 v34, v4, v5
	v_cvt_pk_bf16_f32 v92, v19, v20
	v_cvt_pk_bf16_f32 v93, v21, v22
	v_cvt_pk_bf16_f32 v94, v23, v24
	v_cvt_pk_bf16_f32 v95, v25, v26
	v_cvt_pk_bf16_f32 v96, v27, v28
	v_cvt_pk_bf16_f32 v97, v29, v30
	v_cvt_pk_bf16_f32 v98, v31, v32
	v_cvt_pk_bf16_f32 v99, v33, v34
	global_store_dwordx4 v75, v[92:95], s[0:1]
	global_store_dwordx4 v75, v[96:99], s[0:1] offset:16

.LBB0_197:
	v_add_u32_e32 v60, s0, v23
	ds_read_b128 v[24:27], v21
	ds_read_b128 v[28:31], v22
	ds_read_b128 v[32:35], v22 offset:16
	ds_read_b128 v[36:39], v22 offset:8192
	ds_read_b128 v[40:43], v22 offset:8208
	ds_read_b128 v[44:47], v22 offset:64
	ds_read_b128 v[48:51], v22 offset:80
	ds_read_b128 v[52:55], v22 offset:8256
	ds_read_b128 v[56:59], v22 offset:8272
	ds_read2st64_b64 v[60:63], v60 offset1:8
	s_add_i32 s0, s0, 8
	v_add_u32_e32 v21, 16, v21
	v_add_u32_e32 v22, 0x80, v22
	s_cmpk_eq_i32 s0, 0x100
	s_waitcnt lgkmcnt(0)
	v_mov_b32_e32 v64, v60
	v_mov_b32_e32 v65, v62
	v_mov_b32_e32 v66, v62
	v_mov_b32_e32 v67, v60
	v_mov_b32_e32 v62, v61
	v_mov_b32_e32 v60, v63
	v_pk_mul_f32 v[64:65], v[24:25], v[64:65]
	v_pk_mul_f32 v[24:25], v[24:25], v[66:67]
	v_pk_mul_f32 v[62:63], v[26:27], v[62:63]
	v_pk_mul_f32 v[26:27], v[26:27], v[60:61]
	v_pk_add_f32 v[24:25], v[24:25], v[24:25] op_sel:[1,0] op_sel_hi:[1,0]
	v_pk_add_f32 v[60:61], v[64:65], v[64:65] op_sel:[0,1] op_sel_hi:[0,1] neg_lo:[0,1] neg_hi:[0,1]
	v_pk_add_f32 v[26:27], v[26:27], v[26:27] op_sel:[1,0] op_sel_hi:[1,0]
	v_pk_mul_f32 v[36:37], v[24:25], v[36:37]
	v_pk_mul_f32 v[38:39], v[24:25], v[38:39]
	v_pk_mul_f32 v[40:41], v[24:25], v[40:41]
	v_pk_mul_f32 v[24:25], v[24:25], v[42:43]
	v_pk_add_f32 v[62:63], v[62:63], v[62:63] op_sel:[0,1] op_sel_hi:[0,1] neg_lo:[0,1] neg_hi:[0,1]
	v_pk_mul_f32 v[42:43], v[26:27], v[52:53]
	v_pk_mul_f32 v[52:53], v[26:27], v[54:55]
	v_pk_mul_f32 v[54:55], v[26:27], v[56:57]
	v_pk_mul_f32 v[26:27], v[26:27], v[58:59]
	v_pk_fma_f32 v[28:29], v[28:29], v[60:61], v[36:37] neg_lo:[0,0,1] neg_hi:[0,0,1]
	v_pk_fma_f32 v[30:31], v[60:61], v[30:31], v[38:39] neg_lo:[0,0,1] neg_hi:[0,0,1]
	v_pk_fma_f32 v[32:33], v[60:61], v[32:33], v[40:41] neg_lo:[0,0,1] neg_hi:[0,0,1]
	v_pk_fma_f32 v[24:25], v[60:61], v[34:35], v[24:25] neg_lo:[0,0,1] neg_hi:[0,0,1]
	v_pk_fma_f32 v[34:35], v[44:45], v[62:63], v[42:43] neg_lo:[0,0,1] neg_hi:[0,0,1]
	v_pk_fma_f32 v[36:37], v[62:63], v[46:47], v[52:53] neg_lo:[0,0,1] neg_hi:[0,0,1]
	v_pk_fma_f32 v[38:39], v[62:63], v[48:49], v[54:55] neg_lo:[0,0,1] neg_hi:[0,0,1]
	v_pk_fma_f32 v[26:27], v[62:63], v[50:51], v[26:27] neg_lo:[0,0,1] neg_hi:[0,0,1]
	v_pk_add_f32 v[2:3], v[2:3], v[28:29]
	v_pk_add_f32 v[4:5], v[4:5], v[30:31]
	v_pk_add_f32 v[6:7], v[6:7], v[32:33]
	v_pk_add_f32 v[8:9], v[8:9], v[24:25]
	v_pk_add_f32 v[2:3], v[2:3], v[34:35]
	v_pk_add_f32 v[4:5], v[4:5], v[36:37]
	v_pk_add_f32 v[6:7], v[6:7], v[38:39]
	v_pk_add_f32 v[8:9], v[8:9], v[26:27]
	s_cbranch_scc0 .LBB0_197
	v_lshlrev_b32_e32 v19, 6, v19
	v_lshlrev_b32_e32 v20, 4, v20
	v_and_b32_e32 v12, 8, v12
	v_or3_b32 v10, v20, v19, v10
	v_lshlrev_b32_e32 v10, 6, v10
	v_lshlrev_b32_e32 v19, 2, v12
	s_movk_i32 s0, 0x2000
	v_add3_u32 v10, s41, v10, v19
	v_cmp_gt_i32_e32 vcc, s0, v18
	ds_write_b128 v10, v[2:5] offset:36864
	ds_write_b128 v10, v[6:9] offset:36880
	s_waitcnt lgkmcnt(0)
	s_barrier
	s_and_saveexec_b64 s[6:7], vcc
	s_cbranch_execz .LBB0_106
	s_lshl_b32 s38, s38, 2
	v_and_b32_e32 v2, 1, v18
	v_bfe_u32 v3, v18, 1, 2
	v_bfe_u32 v6, v18, 3, 4
	v_lshrrev_b32_e32 v7, 7, v18
	v_lshlrev_b32_e32 v8, 5, v2
	v_lshl_add_u32 v8, v6, 6, v8
	v_lshl_add_u32 v8, v3, 10, v8
	v_add_u32_e32 v20, s41, v8
	ds_read_b128 v[24:27], v20 offset:36864
	ds_read_b128 v[28:31], v20 offset:36880
	ds_read_b128 v[32:35], v20 offset:40960
	ds_read_b128 v[36:39], v20 offset:40976
	v_add_u32_e32 v9, s38, v3
	v_mul_u32_u24_e32 v8, 0x600, v6
	v_lshl_add_u32 v8, v2, 4, v8
	v_mul_u32_u24_e32 v10, 0x6020, v7
	v_add_u32_e32 v8, v8, v10
	v_lshlrev_b32_e32 v10, 5, v9
	v_sub_u32_e32 v48, v8, v10
	v_add_u32_e32 v49, v8, v10
	v_sub_u32_e32 v50, v7, v9
	v_add_u32_e32 v51, v7, v9
	v_cmp_eq_u32_e32 vcc, 0, v9
	v_mov_b32_e32 v10, 0x4000
	v_cndmask_b32_e32 v51, v51, v10, vcc
	s_waitcnt lgkmcnt(0)
	v_add_f32_e32 v52, v24, v32
	v_add_f32_e32 v53, v25, v33
	v_add_f32_e32 v54, v26, v34
	v_add_f32_e32 v55, v27, v35
	v_add_f32_e32 v56, v28, v36
	v_add_f32_e32 v57, v29, v37
	v_add_f32_e32 v58, v30, v38
	v_add_f32_e32 v59, v31, v39
	v_cndmask_b32_e32 v24, v24, v52, vcc
	v_cndmask_b32_e32 v25, v25, v53, vcc
	v_cndmask_b32_e32 v26, v26, v54, vcc
	v_cndmask_b32_e32 v27, v27, v55, vcc
	v_cndmask_b32_e32 v28, v28, v56, vcc
	v_cndmask_b32_e32 v29, v29, v57, vcc
	v_cndmask_b32_e32 v30, v30, v58, vcc
	v_cndmask_b32_e32 v31, v31, v59, vcc
	v_cvt_pk_bf16_f32 v40, v24, v25
	v_cvt_pk_bf16_f32 v41, v26, v27
	v_cvt_pk_bf16_f32 v42, v28, v29
	v_cvt_pk_bf16_f32 v43, v30, v31
	v_cvt_pk_bf16_f32 v44, v32, v33
	v_cvt_pk_bf16_f32 v45, v34, v35
	v_cvt_pk_bf16_f32 v46, v36, v37
	v_cvt_pk_bf16_f32 v47, v38, v39
	v_cmp_le_i32_e32 vcc, 0, v50
	v_mov_b32_e32 v22, v48
	s_mov_b64 exec, vcc
	global_store_dwordx4 v22, v[40:43], s[4:5]
	s_mov_b64 exec, -1
	v_cmp_ge_i32_e32 vcc, 31, v51
	v_mov_b32_e32 v23, v49
	s_mov_b64 exec, vcc
	global_store_dwordx4 v23, v[44:47], s[4:5]
	s_mov_b64 exec, -1
	v_cmp_le_i32_e32 vcc, -2, v50
	v_add_u32_e32 v22, 0xc040, v48
	s_mov_b64 exec, vcc
	global_store_dwordx4 v22, v[40:43], s[4:5]
	s_mov_b64 exec, -1
	v_cmp_ge_i32_e32 vcc, 29, v51
	v_add_u32_e32 v23, 0xc040, v49
	s_mov_b64 exec, vcc
	global_store_dwordx4 v23, v[44:47], s[4:5]
	s_mov_b64 exec, -1
	v_cmp_le_i32_e32 vcc, -4, v50
	v_add_u32_e32 v22, 0x18080, v48
	s_mov_b64 exec, vcc
	global_store_dwordx4 v22, v[40:43], s[4:5]
	s_mov_b64 exec, -1
	v_cmp_ge_i32_e32 vcc, 27, v51
	v_add_u32_e32 v23, 0x18080, v49
	s_mov_b64 exec, vcc
	global_store_dwordx4 v23, v[44:47], s[4:5]
	s_mov_b64 exec, -1
	v_cmp_le_i32_e32 vcc, -6, v50
	v_add_u32_e32 v22, 0x240c0, v48
	s_mov_b64 exec, vcc
	global_store_dwordx4 v22, v[40:43], s[4:5]
	s_mov_b64 exec, -1
	v_cmp_ge_i32_e32 vcc, 25, v51
	v_add_u32_e32 v23, 0x240c0, v49
	s_mov_b64 exec, vcc
	global_store_dwordx4 v23, v[44:47], s[4:5]
	s_mov_b64 exec, -1
	v_cmp_le_i32_e32 vcc, -8, v50
	v_add_u32_e32 v22, 0x30100, v48
	s_mov_b64 exec, vcc
	global_store_dwordx4 v22, v[40:43], s[4:5]
	s_mov_b64 exec, -1
	v_cmp_ge_i32_e32 vcc, 23, v51
	v_add_u32_e32 v23, 0x30100, v49
	s_mov_b64 exec, vcc
	global_store_dwordx4 v23, v[44:47], s[4:5]
	s_mov_b64 exec, -1
	v_cmp_le_i32_e32 vcc, -10, v50
	v_add_u32_e32 v22, 0x3c140, v48
	s_mov_b64 exec, vcc
	global_store_dwordx4 v22, v[40:43], s[4:5]
	s_mov_b64 exec, -1
	v_cmp_ge_i32_e32 vcc, 21, v51
	v_add_u32_e32 v23, 0x3c140, v49
	s_mov_b64 exec, vcc
	global_store_dwordx4 v23, v[44:47], s[4:5]
	s_mov_b64 exec, -1
	v_cmp_le_i32_e32 vcc, -12, v50
	v_add_u32_e32 v22, 0x48180, v48
	s_mov_b64 exec, vcc
	global_store_dwordx4 v22, v[40:43], s[4:5]
	s_mov_b64 exec, -1
	v_cmp_ge_i32_e32 vcc, 19, v51
	v_add_u32_e32 v23, 0x48180, v49
	s_mov_b64 exec, vcc
	global_store_dwordx4 v23, v[44:47], s[4:5]
	s_mov_b64 exec, -1
	v_cmp_le_i32_e32 vcc, -14, v50
	v_add_u32_e32 v22, 0x541c0, v48
	s_mov_b64 exec, vcc
	global_store_dwordx4 v22, v[40:43], s[4:5]
	s_mov_b64 exec, -1
	v_cmp_ge_i32_e32 vcc, 17, v51
	v_add_u32_e32 v23, 0x541c0, v49
	s_mov_b64 exec, vcc
	global_store_dwordx4 v23, v[44:47], s[4:5]
	s_mov_b64 exec, -1
	v_cmp_le_i32_e32 vcc, -16, v50
	v_add_u32_e32 v22, 0x60200, v48
	s_mov_b64 exec, vcc
	global_store_dwordx4 v22, v[40:43], s[4:5]
	s_mov_b64 exec, -1
	v_cmp_ge_i32_e32 vcc, 15, v51
	v_add_u32_e32 v23, 0x60200, v49
	s_mov_b64 exec, vcc
	global_store_dwordx4 v23, v[44:47], s[4:5]
	s_mov_b64 exec, -1
	v_cmp_le_i32_e32 vcc, -18, v50
	v_add_u32_e32 v22, 0x6c240, v48
	s_mov_b64 exec, vcc
	global_store_dwordx4 v22, v[40:43], s[4:5]
	s_mov_b64 exec, -1
	v_cmp_ge_i32_e32 vcc, 13, v51
	v_add_u32_e32 v23, 0x6c240, v49
	s_mov_b64 exec, vcc
	global_store_dwordx4 v23, v[44:47], s[4:5]
	s_mov_b64 exec, -1
	v_cmp_le_i32_e32 vcc, -20, v50
	v_add_u32_e32 v22, 0x78280, v48
	s_mov_b64 exec, vcc
	global_store_dwordx4 v22, v[40:43], s[4:5]
	s_mov_b64 exec, -1
	v_cmp_ge_i32_e32 vcc, 11, v51
	v_add_u32_e32 v23, 0x78280, v49
	s_mov_b64 exec, vcc
	global_store_dwordx4 v23, v[44:47], s[4:5]
	s_mov_b64 exec, -1
	v_cmp_le_i32_e32 vcc, -22, v50
	v_add_u32_e32 v22, 0x842c0, v48
	s_mov_b64 exec, vcc
	global_store_dwordx4 v22, v[40:43], s[4:5]
	s_mov_b64 exec, -1
	v_cmp_ge_i32_e32 vcc, 9, v51
	v_add_u32_e32 v23, 0x842c0, v49
	s_mov_b64 exec, vcc
	global_store_dwordx4 v23, v[44:47], s[4:5]
	s_mov_b64 exec, -1
	v_cmp_le_i32_e32 vcc, -24, v50
	v_add_u32_e32 v22, 0x90300, v48
	s_mov_b64 exec, vcc
	global_store_dwordx4 v22, v[40:43], s[4:5]
	s_mov_b64 exec, -1
	v_cmp_ge_i32_e32 vcc, 7, v51
	v_add_u32_e32 v23, 0x90300, v49
	s_mov_b64 exec, vcc
	global_store_dwordx4 v23, v[44:47], s[4:5]
	s_mov_b64 exec, -1
	v_cmp_le_i32_e32 vcc, -26, v50
	v_add_u32_e32 v22, 0x9c340, v48
	s_mov_b64 exec, vcc
	global_store_dwordx4 v22, v[40:43], s[4:5]
	s_mov_b64 exec, -1
	v_cmp_ge_i32_e32 vcc, 5, v51
	v_add_u32_e32 v23, 0x9c340, v49
	s_mov_b64 exec, vcc
	global_store_dwordx4 v23, v[44:47], s[4:5]
	s_mov_b64 exec, -1
	v_cmp_le_i32_e32 vcc, -28, v50
	v_add_u32_e32 v22, 0xa8380, v48
	s_mov_b64 exec, vcc
	global_store_dwordx4 v22, v[40:43], s[4:5]
	s_mov_b64 exec, -1
	v_cmp_ge_i32_e32 vcc, 3, v51
	v_add_u32_e32 v23, 0xa8380, v49
	s_mov_b64 exec, vcc
	global_store_dwordx4 v23, v[44:47], s[4:5]
	s_mov_b64 exec, -1
	v_cmp_le_i32_e32 vcc, -30, v50
	v_add_u32_e32 v22, 0xb43c0, v48
	s_mov_b64 exec, vcc
	global_store_dwordx4 v22, v[40:43], s[4:5]
	s_mov_b64 exec, -1
	v_cmp_ge_i32_e32 vcc, 1, v51
	v_add_u32_e32 v23, 0xb43c0, v49
	s_mov_b64 exec, vcc
	global_store_dwordx4 v23, v[44:47], s[4:5]
	s_mov_b64 exec, -1
	s_branch .LBB0_106
